# diff-attn: uniform-bias fast path per sub-tile, pipelined PV+QK LDS reads, permlane max, setprio 3 on softmax segments
# speedup vs baseline: 1.0333x; 1.0200x over previous
; #define LAS __attribute__((address_space(3)))
; __device__ __forceinline__ unsigned pk2(float lo, float hi) { v2f v = {lo, hi}; return __builtin_bit_cast(unsigned, __builtin_convertvector(v, v2bf)); }
; __device__ __forceinline__ void d2_softmax(v16f& S, const float c1, const LAS float* tp, float& m, float& l, v16f (&O)[4], v8s (&P)[2]) {
;     float tmax = NEGBIG;
; #pragma unroll
;     for (int i = 0; i < 16; ++i) { S[i] = S[i] * c1 + tp[(i & 3) + 8 * (i >> 2)]; tmax = fmaxf(tmax, S[i]); }
;     tmax = fmaxf(tmax, __shfl_xor(tmax, 32));
;     const float mo = m;
;     if (__any(tmax > mo + 8.f)) {
;         const float mn = (tmax > mo + 8.f) ? tmax : mo;
;         const float alpha = __builtin_amdgcn_exp2f(mo - mn);
;         l *= alpha;
; #pragma unroll
;         for (int eb = 0; eb < 4; ++eb)
; #pragma unroll
;             for (int i = 0; i < 16; ++i) O[eb][i] *= alpha;
;         m = mn;
;     }
;     const float mc = m;
;     float ps = 0.f;
; #pragma unroll
;     for (int i = 0; i < 16; ++i) { S[i] = __builtin_amdgcn_exp2f(S[i] - mc); ps += S[i]; }
;     l += ps;
; #pragma unroll
;     for (int s2 = 0; s2 < 2; ++s2) { v4u w; w.x = pk2(S[8 * s2 + 0], S[8 * s2 + 1]); w.y = pk2(S[8 * s2 + 2], S[8 * s2 + 3]); w.z = pk2(S[8 * s2 + 4], S[8 * s2 + 5]); w.w = pk2(S[8 * s2 + 6], S[8 * s2 + 7]);
;         P[s2] = __builtin_bit_cast(v8s, w); }
; }
.LBB0_335:
	s_andn2_saveexec_b64 s[18:19], s[10:11]
	s_cbranch_execz .LBB0_341
	s_setprio 3
	v_readfirstlane_b32 s98, v183
	v_med3_i32 v0, v183, s16, v214
	v_add_u32_e32 v156, 32, v183
	s_mov_b32 s100, 0xfff9f990
	s_mov_b32 s101, -1
	v_lshl_add_u32 v0, v0, 2, s23
	v_med3_i32 v156, v156, s16, v214
	s_add_i32 s99, s98, 32
	s_abs_i32 s98, s98
	s_abs_i32 s99, s99
	s_lshr_b32 s98, s98, 5
	s_lshr_b32 s99, s99, 5
	v_add_u32_e32 v0, 0xa80, v0
	v_lshl_add_u32 v156, v156, 2, s23
	v_add_u32_e32 v156, 0xa80, v156
	s_bitcmp1_b64 s[100:101], s99
	s_cbranch_scc1 .Ld2x0_i1f
	ds_read2_b32 v[186:187], v156 offset1:1
	ds_read2_b32 v[188:189], v156 offset0:2 offset1:3
	ds_read2_b32 v[190:191], v156 offset0:8 offset1:9
	ds_read2_b32 v[192:193], v156 offset0:10 offset1:11
	ds_read2_b32 v[194:195], v156 offset0:16 offset1:17
	ds_read2_b32 v[196:197], v156 offset0:18 offset1:19
	ds_read2_b32 v[198:199], v156 offset0:24 offset1:25
	ds_read2_b32 v[200:201], v156 offset0:26 offset1:27
	s_branch .Ld2x0_i1d
.Ld2x0_i1f:
	ds_read_b32 v186, v156
.Ld2x0_i1d:
	s_bitcmp1_b64 s[100:101], s98
	s_cbranch_scc1 .Ld2x0_c0f
	ds_read2_b32 v[134:135], v0 offset1:1
	ds_read2_b32 v[130:131], v0 offset0:2 offset1:3
	ds_read2_b32 v[132:133], v0 offset0:8 offset1:9
	ds_read2_b32 v[136:137], v0 offset0:10 offset1:11
	ds_read2_b32 v[138:139], v0 offset0:16 offset1:17
	ds_read2_b32 v[140:141], v0 offset0:18 offset1:19
	ds_read2_b32 v[142:143], v0 offset0:24 offset1:25
	s_waitcnt lgkmcnt(6)
	ds_read2_b32 v[144:145], v0 offset0:26 offset1:27
	v_fmac_f32_e32 v135, 0x3e38aa3b, v67
	v_fmamk_f32 v0, v66, 0x3e38aa3b, v134
	v_max3_f32 v66, v0, s15, v135
	s_waitcnt lgkmcnt(6)
	v_fmamk_f32 v68, v68, 0x3e38aa3b, v130
	v_fmac_f32_e32 v131, 0x3e38aa3b, v69
	v_max3_f32 v66, v66, v68, v131
	s_waitcnt lgkmcnt(5)
	v_fmamk_f32 v70, v70, 0x3e38aa3b, v132
	v_fmac_f32_e32 v133, 0x3e38aa3b, v71
	v_max3_f32 v66, v66, v70, v133
	s_waitcnt lgkmcnt(4)
	v_fmamk_f32 v72, v72, 0x3e38aa3b, v136
	v_fmac_f32_e32 v137, 0x3e38aa3b, v73
	v_max3_f32 v66, v66, v72, v137
	s_waitcnt lgkmcnt(3)
	v_fmamk_f32 v74, v74, 0x3e38aa3b, v138
	v_fmac_f32_e32 v139, 0x3e38aa3b, v75
	v_max3_f32 v66, v66, v74, v139
	s_waitcnt lgkmcnt(2)
	v_fmamk_f32 v76, v76, 0x3e38aa3b, v140
	v_fmac_f32_e32 v141, 0x3e38aa3b, v77
	v_max3_f32 v66, v66, v76, v141
	s_waitcnt lgkmcnt(1)
	v_fmamk_f32 v78, v78, 0x3e38aa3b, v142
	v_fmac_f32_e32 v143, 0x3e38aa3b, v79
	v_max3_f32 v66, v66, v78, v143
	s_waitcnt lgkmcnt(0)
	v_fmamk_f32 v80, v80, 0x3e38aa3b, v144
	v_fmac_f32_e32 v145, 0x3e38aa3b, v81
	v_max3_f32 v66, v66, v80, v145
	v_add_f32_e32 v130, 0x41000000, v184
	v_mov_b32_e32 v67, v66
	s_nop 1
	v_permlane32_swap_b32_e32 v67, v66
	v_max_f32_e32 v66, v66, v67
	v_cmp_gt_f32_e32 vcc, v66, v130
	s_cbranch_vccz .Ld2x0_a
	s_nop 0
	v_cndmask_b32_e32 v67, v184, v66, vcc
	v_sub_f32_e32 v66, v184, v67
	v_exp_f32_e32 v66, v66
	v_add_f32_e32 v130, 0x41000000, v67
	v_mov_b32_e32 v184, v67
	v_mul_f32_e32 v154, v154, v66
	v_pk_mul_f32 v[64:65], v[64:65], v[66:67] op_sel_hi:[1,0]
	v_pk_mul_f32 v[62:63], v[62:63], v[66:67] op_sel_hi:[1,0]
	v_pk_mul_f32 v[60:61], v[60:61], v[66:67] op_sel_hi:[1,0]
	v_pk_mul_f32 v[58:59], v[58:59], v[66:67] op_sel_hi:[1,0]
	v_pk_mul_f32 v[56:57], v[56:57], v[66:67] op_sel_hi:[1,0]
	v_pk_mul_f32 v[54:55], v[54:55], v[66:67] op_sel_hi:[1,0]
	v_pk_mul_f32 v[52:53], v[52:53], v[66:67] op_sel_hi:[1,0]
	v_pk_mul_f32 v[50:51], v[50:51], v[66:67] op_sel_hi:[1,0]
	v_pk_mul_f32 v[48:49], v[48:49], v[66:67] op_sel_hi:[1,0]
	v_pk_mul_f32 v[46:47], v[46:47], v[66:67] op_sel_hi:[1,0]
	v_pk_mul_f32 v[44:45], v[44:45], v[66:67] op_sel_hi:[1,0]
	v_pk_mul_f32 v[42:43], v[42:43], v[66:67] op_sel_hi:[1,0]
	v_pk_mul_f32 v[40:41], v[40:41], v[66:67] op_sel_hi:[1,0]
	v_pk_mul_f32 v[38:39], v[38:39], v[66:67] op_sel_hi:[1,0]
	v_pk_mul_f32 v[36:37], v[36:37], v[66:67] op_sel_hi:[1,0]
	v_pk_mul_f32 v[34:35], v[34:35], v[66:67] op_sel_hi:[1,0]
	v_pk_mul_f32 v[32:33], v[32:33], v[66:67] op_sel_hi:[1,0]
	v_pk_mul_f32 v[30:31], v[30:31], v[66:67] op_sel_hi:[1,0]
	v_pk_mul_f32 v[28:29], v[28:29], v[66:67] op_sel_hi:[1,0]
	v_pk_mul_f32 v[26:27], v[26:27], v[66:67] op_sel_hi:[1,0]
	v_pk_mul_f32 v[24:25], v[24:25], v[66:67] op_sel_hi:[1,0]
	v_pk_mul_f32 v[22:23], v[22:23], v[66:67] op_sel_hi:[1,0]
	v_pk_mul_f32 v[20:21], v[20:21], v[66:67] op_sel_hi:[1,0]
	v_pk_mul_f32 v[18:19], v[18:19], v[66:67] op_sel_hi:[1,0]
	v_pk_mul_f32 v[16:17], v[16:17], v[66:67] op_sel_hi:[1,0]
	v_pk_mul_f32 v[14:15], v[14:15], v[66:67] op_sel_hi:[1,0]
	v_pk_mul_f32 v[12:13], v[12:13], v[66:67] op_sel_hi:[1,0]
	v_pk_mul_f32 v[10:11], v[10:11], v[66:67] op_sel_hi:[1,0]
	v_pk_mul_f32 v[8:9], v[8:9], v[66:67] op_sel_hi:[1,0]
	v_pk_mul_f32 v[6:7], v[6:7], v[66:67] op_sel_hi:[1,0]
	v_pk_mul_f32 v[4:5], v[4:5], v[66:67] op_sel_hi:[1,0]
	v_pk_mul_f32 v[2:3], v[2:3], v[66:67] op_sel_hi:[1,0]
.Ld2x0_a:
	v_sub_f32_e32 v66, v0, v184
	v_exp_f32_e32 v66, v66
	v_sub_f32_e32 v67, v135, v184
	v_exp_f32_e32 v67, v67
	v_sub_f32_e32 v68, v68, v184
	v_exp_f32_e32 v68, v68
	v_sub_f32_e32 v69, v131, v184
	v_exp_f32_e32 v69, v69
	v_sub_f32_e32 v70, v70, v184
	v_add_f32_e32 v0, 0, v66
	v_exp_f32_e32 v70, v70
	v_sub_f32_e32 v71, v133, v184
	v_add_f32_e32 v0, v67, v0
	v_exp_f32_e32 v71, v71
	v_sub_f32_e32 v72, v72, v184
	v_add_f32_e32 v0, v68, v0
	v_exp_f32_e32 v72, v72
	v_sub_f32_e32 v73, v137, v184
	v_add_f32_e32 v0, v69, v0
	v_exp_f32_e32 v73, v73
	v_sub_f32_e32 v74, v74, v184
	v_add_f32_e32 v0, v70, v0
	v_exp_f32_e32 v74, v74
	v_sub_f32_e32 v75, v139, v184
	v_add_f32_e32 v0, v71, v0
	v_exp_f32_e32 v75, v75
	v_sub_f32_e32 v76, v76, v184
	v_add_f32_e32 v0, v72, v0
	v_exp_f32_e32 v76, v76
	v_sub_f32_e32 v77, v141, v184
	v_add_f32_e32 v0, v73, v0
	v_exp_f32_e32 v77, v77
	v_sub_f32_e32 v78, v78, v184
	v_add_f32_e32 v0, v74, v0
	v_exp_f32_e32 v78, v78
	v_sub_f32_e32 v79, v143, v184
	v_add_f32_e32 v0, v75, v0
	v_exp_f32_e32 v79, v79
	v_sub_f32_e32 v80, v80, v184
	v_add_f32_e32 v0, v76, v0
	v_exp_f32_e32 v80, v80
	v_sub_f32_e32 v81, v145, v184
	v_add_f32_e32 v0, v77, v0
	v_exp_f32_e32 v81, v81
	s_branch .Ld2x0_s0t
; #define LAS __attribute__((address_space(3)))
; __device__ __forceinline__ unsigned pk2(float lo, float hi) { v2f v = {lo, hi}; return __builtin_bit_cast(unsigned, __builtin_convertvector(v, v2bf)); }
; __device__ __forceinline__ void d2_softmax(v16f& S, const float c1, const LAS float* tp, float& m, float& l, v16f (&O)[4], v8s (&P)[2]) {
;     float tmax = NEGBIG;
; #pragma unroll
;     for (int i = 0; i < 16; ++i) { S[i] = S[i] * c1 + tp[(i & 3) + 8 * (i >> 2)]; tmax = fmaxf(tmax, S[i]); }
;     tmax = fmaxf(tmax, __shfl_xor(tmax, 32));
;     const float mo = m;
;     if (__any(tmax > mo + 8.f)) {
;         const float mn = (tmax > mo + 8.f) ? tmax : mo;
;         const float alpha = __builtin_amdgcn_exp2f(mo - mn);
;         l *= alpha;
; #pragma unroll
;         for (int eb = 0; eb < 4; ++eb)
; #pragma unroll
;             for (int i = 0; i < 16; ++i) O[eb][i] *= alpha;
;         m = mn;
;     }
;     const float mc = m;
;     float ps = 0.f;
; #pragma unroll
;     for (int i = 0; i < 16; ++i) { S[i] = __builtin_amdgcn_exp2f(S[i] - mc); ps += S[i]; }
;     l += ps;
; #pragma unroll
;     for (int s2 = 0; s2 < 2; ++s2) { v4u w; w.x = pk2(S[8 * s2 + 0], S[8 * s2 + 1]); w.y = pk2(S[8 * s2 + 2], S[8 * s2 + 3]); w.z = pk2(S[8 * s2 + 4], S[8 * s2 + 5]); w.w = pk2(S[8 * s2 + 6], S[8 * s2 + 7]);
;         P[s2] = __builtin_bit_cast(v8s, w); }
; }
.Ld2x0_c0f:
	ds_read_b32 v134, v0
	v_max3_f32 v135, v66, v67, v68
	v_max3_f32 v135, v135, v69, v70
	v_max3_f32 v135, v135, v71, v72
	v_max3_f32 v135, v135, v73, v74
	v_max3_f32 v135, v135, v75, v76
	v_max3_f32 v135, v135, v77, v78
	v_max3_f32 v135, v135, v79, v80
	v_max_f32_e32 v135, v135, v81
	v_add_f32_e32 v130, 0x41000000, v184
	s_waitcnt lgkmcnt(0)
	v_fmamk_f32 v135, v135, 0x3e38aa3b, v134
	v_mov_b32_e32 v136, v135
	s_nop 1
	v_permlane32_swap_b32_e32 v136, v135
	v_max_f32_e32 v135, v135, v136
	v_cmp_gt_f32_e32 vcc, v135, v130
	s_cbranch_vccz .Ld2x0_f0a
	s_nop 0
	v_cndmask_b32_e32 v137, v184, v135, vcc
	v_sub_f32_e32 v136, v184, v137
	v_exp_f32_e32 v136, v136
	v_add_f32_e32 v130, 0x41000000, v137
	v_mov_b32_e32 v184, v137
	v_mul_f32_e32 v154, v154, v136
	v_pk_mul_f32 v[64:65], v[64:65], v[136:137] op_sel_hi:[1,0]
	v_pk_mul_f32 v[62:63], v[62:63], v[136:137] op_sel_hi:[1,0]
	v_pk_mul_f32 v[60:61], v[60:61], v[136:137] op_sel_hi:[1,0]
	v_pk_mul_f32 v[58:59], v[58:59], v[136:137] op_sel_hi:[1,0]
	v_pk_mul_f32 v[56:57], v[56:57], v[136:137] op_sel_hi:[1,0]
	v_pk_mul_f32 v[54:55], v[54:55], v[136:137] op_sel_hi:[1,0]
	v_pk_mul_f32 v[52:53], v[52:53], v[136:137] op_sel_hi:[1,0]
	v_pk_mul_f32 v[50:51], v[50:51], v[136:137] op_sel_hi:[1,0]
	v_pk_mul_f32 v[48:49], v[48:49], v[136:137] op_sel_hi:[1,0]
	v_pk_mul_f32 v[46:47], v[46:47], v[136:137] op_sel_hi:[1,0]
	v_pk_mul_f32 v[44:45], v[44:45], v[136:137] op_sel_hi:[1,0]
	v_pk_mul_f32 v[42:43], v[42:43], v[136:137] op_sel_hi:[1,0]
	v_pk_mul_f32 v[40:41], v[40:41], v[136:137] op_sel_hi:[1,0]
	v_pk_mul_f32 v[38:39], v[38:39], v[136:137] op_sel_hi:[1,0]
	v_pk_mul_f32 v[36:37], v[36:37], v[136:137] op_sel_hi:[1,0]
	v_pk_mul_f32 v[34:35], v[34:35], v[136:137] op_sel_hi:[1,0]
	v_pk_mul_f32 v[32:33], v[32:33], v[136:137] op_sel_hi:[1,0]
	v_pk_mul_f32 v[30:31], v[30:31], v[136:137] op_sel_hi:[1,0]
	v_pk_mul_f32 v[28:29], v[28:29], v[136:137] op_sel_hi:[1,0]
	v_pk_mul_f32 v[26:27], v[26:27], v[136:137] op_sel_hi:[1,0]
	v_pk_mul_f32 v[24:25], v[24:25], v[136:137] op_sel_hi:[1,0]
	v_pk_mul_f32 v[22:23], v[22:23], v[136:137] op_sel_hi:[1,0]
	v_pk_mul_f32 v[20:21], v[20:21], v[136:137] op_sel_hi:[1,0]
	v_pk_mul_f32 v[18:19], v[18:19], v[136:137] op_sel_hi:[1,0]
	v_pk_mul_f32 v[16:17], v[16:17], v[136:137] op_sel_hi:[1,0]
	v_pk_mul_f32 v[14:15], v[14:15], v[136:137] op_sel_hi:[1,0]
	v_pk_mul_f32 v[12:13], v[12:13], v[136:137] op_sel_hi:[1,0]
	v_pk_mul_f32 v[10:11], v[10:11], v[136:137] op_sel_hi:[1,0]
	v_pk_mul_f32 v[8:9], v[8:9], v[136:137] op_sel_hi:[1,0]
	v_pk_mul_f32 v[6:7], v[6:7], v[136:137] op_sel_hi:[1,0]
	v_pk_mul_f32 v[4:5], v[4:5], v[136:137] op_sel_hi:[1,0]
	v_pk_mul_f32 v[2:3], v[2:3], v[136:137] op_sel_hi:[1,0]
.Ld2x0_f0a:
	v_sub_f32_e32 v134, v134, v184
	v_fmamk_f32 v66, v66, 0x3e38aa3b, v134
	v_exp_f32_e32 v66, v66
	v_fmamk_f32 v67, v67, 0x3e38aa3b, v134
	v_exp_f32_e32 v67, v67
	v_fmamk_f32 v68, v68, 0x3e38aa3b, v134
	v_exp_f32_e32 v68, v68
	v_fmamk_f32 v69, v69, 0x3e38aa3b, v134
	v_exp_f32_e32 v69, v69
	v_fmamk_f32 v70, v70, 0x3e38aa3b, v134
	v_add_f32_e32 v0, 0, v66
	v_exp_f32_e32 v70, v70
	v_fmamk_f32 v71, v71, 0x3e38aa3b, v134
	v_add_f32_e32 v0, v67, v0
	v_exp_f32_e32 v71, v71
	v_fmamk_f32 v72, v72, 0x3e38aa3b, v134
	v_add_f32_e32 v0, v68, v0
	v_exp_f32_e32 v72, v72
	v_fmamk_f32 v73, v73, 0x3e38aa3b, v134
	v_add_f32_e32 v0, v69, v0
	v_exp_f32_e32 v73, v73
	v_fmamk_f32 v74, v74, 0x3e38aa3b, v134
	v_add_f32_e32 v0, v70, v0
	v_exp_f32_e32 v74, v74
	v_fmamk_f32 v75, v75, 0x3e38aa3b, v134
	v_add_f32_e32 v0, v71, v0
	v_exp_f32_e32 v75, v75
	v_fmamk_f32 v76, v76, 0x3e38aa3b, v134
	v_add_f32_e32 v0, v72, v0
	v_exp_f32_e32 v76, v76
	v_fmamk_f32 v77, v77, 0x3e38aa3b, v134
	v_add_f32_e32 v0, v73, v0
	v_exp_f32_e32 v77, v77
	v_fmamk_f32 v78, v78, 0x3e38aa3b, v134
	v_add_f32_e32 v0, v74, v0
	v_exp_f32_e32 v78, v78
	v_fmamk_f32 v79, v79, 0x3e38aa3b, v134
	v_add_f32_e32 v0, v75, v0
	v_exp_f32_e32 v79, v79
	v_fmamk_f32 v80, v80, 0x3e38aa3b, v134
	v_add_f32_e32 v0, v76, v0
	v_exp_f32_e32 v80, v80
	v_fmamk_f32 v81, v81, 0x3e38aa3b, v134
	v_add_f32_e32 v0, v77, v0
	v_exp_f32_e32 v81, v81
.Ld2x0_s0t:
	v_add_f32_e32 v0, v78, v0
	v_add_f32_e32 v0, v79, v0
	v_add_f32_e32 v0, v80, v0
	v_add_f32_e32 v0, v81, v0
	v_add_f32_e32 v0, v154, v0
	s_waitcnt lgkmcnt(0)
	s_bitcmp1_b64 s[100:101], s99
	s_cbranch_scc1 .Ld2x0_c1f
	v_fmamk_f32 v82, v82, 0x3e38aa3b, v186
	v_fmac_f32_e32 v187, 0x3e38aa3b, v83
	v_max3_f32 v83, v82, s15, v187
	v_fmamk_f32 v84, v84, 0x3e38aa3b, v188
	v_fmac_f32_e32 v189, 0x3e38aa3b, v85
	v_max3_f32 v83, v83, v84, v189
	v_fmamk_f32 v86, v86, 0x3e38aa3b, v190
	v_fmac_f32_e32 v191, 0x3e38aa3b, v87
	v_max3_f32 v83, v83, v86, v191
	v_fmamk_f32 v88, v88, 0x3e38aa3b, v192
	v_fmac_f32_e32 v193, 0x3e38aa3b, v89
	v_max3_f32 v83, v83, v88, v193
	v_fmamk_f32 v90, v90, 0x3e38aa3b, v194
	v_fmac_f32_e32 v195, 0x3e38aa3b, v91
	v_max3_f32 v83, v83, v90, v195
	v_fmamk_f32 v92, v92, 0x3e38aa3b, v196
	v_fmac_f32_e32 v197, 0x3e38aa3b, v93
	v_max3_f32 v83, v83, v92, v197
	v_fmamk_f32 v94, v94, 0x3e38aa3b, v198
	v_fmac_f32_e32 v199, 0x3e38aa3b, v95
	v_max3_f32 v83, v83, v94, v199
	v_fmamk_f32 v96, v96, 0x3e38aa3b, v200
	v_fmac_f32_e32 v201, 0x3e38aa3b, v97
	v_max3_f32 v83, v83, v96, v201
	v_mov_b32_e32 v85, v83
	s_nop 1
	v_permlane32_swap_b32_e32 v85, v83
	v_max_f32_e32 v83, v83, v85
	v_cmp_gt_f32_e32 vcc, v83, v130
	s_cbranch_vccz .Ld2x0_b
; #define LAS __attribute__((address_space(3)))
; __device__ __forceinline__ unsigned pk2(float lo, float hi) { v2f v = {lo, hi}; return __builtin_bit_cast(unsigned, __builtin_convertvector(v, v2bf)); }
; __device__ __forceinline__ void d2_softmax(v16f& S, const float c1, const LAS float* tp, float& m, float& l, v16f (&O)[4], v8s (&P)[2]) {
;     float tmax = NEGBIG;
; #pragma unroll
;     for (int i = 0; i < 16; ++i) { S[i] = S[i] * c1 + tp[(i & 3) + 8 * (i >> 2)]; tmax = fmaxf(tmax, S[i]); }
;     tmax = fmaxf(tmax, __shfl_xor(tmax, 32));
;     const float mo = m;
;     if (__any(tmax > mo + 8.f)) {
;         const float mn = (tmax > mo + 8.f) ? tmax : mo;
;         const float alpha = __builtin_amdgcn_exp2f(mo - mn);
;         l *= alpha;
; #pragma unroll
;         for (int eb = 0; eb < 4; ++eb)
; #pragma unroll
;             for (int i = 0; i < 16; ++i) O[eb][i] *= alpha;
;         m = mn;
;     }
;     const float mc = m;
;     float ps = 0.f;
; #pragma unroll
;     for (int i = 0; i < 16; ++i) { S[i] = __builtin_amdgcn_exp2f(S[i] - mc); ps += S[i]; }
;     l += ps;
; #pragma unroll
;     for (int s2 = 0; s2 < 2; ++s2) { v4u w; w.x = pk2(S[8 * s2 + 0], S[8 * s2 + 1]); w.y = pk2(S[8 * s2 + 2], S[8 * s2 + 3]); w.z = pk2(S[8 * s2 + 4], S[8 * s2 + 5]); w.w = pk2(S[8 * s2 + 6], S[8 * s2 + 7]);
;         P[s2] = __builtin_bit_cast(v8s, w); }
; }
	s_nop 0
	v_cndmask_b32_e32 v83, v184, v83, vcc
	v_sub_f32_e32 v85, v184, v83
	v_exp_f32_e32 v130, v85
	v_mov_b32_e32 v184, v83
	v_mul_f32_e32 v0, v0, v130
	v_pk_mul_f32 v[64:65], v[64:65], v[130:131] op_sel_hi:[1,0]
	v_pk_mul_f32 v[62:63], v[62:63], v[130:131] op_sel_hi:[1,0]
	v_pk_mul_f32 v[60:61], v[60:61], v[130:131] op_sel_hi:[1,0]
	v_pk_mul_f32 v[58:59], v[58:59], v[130:131] op_sel_hi:[1,0]
	v_pk_mul_f32 v[56:57], v[56:57], v[130:131] op_sel_hi:[1,0]
	v_pk_mul_f32 v[54:55], v[54:55], v[130:131] op_sel_hi:[1,0]
	v_pk_mul_f32 v[52:53], v[52:53], v[130:131] op_sel_hi:[1,0]
	v_pk_mul_f32 v[50:51], v[50:51], v[130:131] op_sel_hi:[1,0]
	v_pk_mul_f32 v[48:49], v[48:49], v[130:131] op_sel_hi:[1,0]
	v_pk_mul_f32 v[46:47], v[46:47], v[130:131] op_sel_hi:[1,0]
	v_pk_mul_f32 v[44:45], v[44:45], v[130:131] op_sel_hi:[1,0]
	v_pk_mul_f32 v[42:43], v[42:43], v[130:131] op_sel_hi:[1,0]
	v_pk_mul_f32 v[40:41], v[40:41], v[130:131] op_sel_hi:[1,0]
	v_pk_mul_f32 v[38:39], v[38:39], v[130:131] op_sel_hi:[1,0]
	v_pk_mul_f32 v[36:37], v[36:37], v[130:131] op_sel_hi:[1,0]
	v_pk_mul_f32 v[34:35], v[34:35], v[130:131] op_sel_hi:[1,0]
	v_pk_mul_f32 v[32:33], v[32:33], v[130:131] op_sel_hi:[1,0]
	v_pk_mul_f32 v[30:31], v[30:31], v[130:131] op_sel_hi:[1,0]
	v_pk_mul_f32 v[28:29], v[28:29], v[130:131] op_sel_hi:[1,0]
	v_pk_mul_f32 v[26:27], v[26:27], v[130:131] op_sel_hi:[1,0]
	v_pk_mul_f32 v[24:25], v[24:25], v[130:131] op_sel_hi:[1,0]
	v_pk_mul_f32 v[22:23], v[22:23], v[130:131] op_sel_hi:[1,0]
	v_pk_mul_f32 v[20:21], v[20:21], v[130:131] op_sel_hi:[1,0]
	v_pk_mul_f32 v[18:19], v[18:19], v[130:131] op_sel_hi:[1,0]
	v_pk_mul_f32 v[16:17], v[16:17], v[130:131] op_sel_hi:[1,0]
	v_pk_mul_f32 v[14:15], v[14:15], v[130:131] op_sel_hi:[1,0]
	v_pk_mul_f32 v[12:13], v[12:13], v[130:131] op_sel_hi:[1,0]
	v_pk_mul_f32 v[10:11], v[10:11], v[130:131] op_sel_hi:[1,0]
	v_pk_mul_f32 v[8:9], v[8:9], v[130:131] op_sel_hi:[1,0]
	v_pk_mul_f32 v[6:7], v[6:7], v[130:131] op_sel_hi:[1,0]
	v_pk_mul_f32 v[4:5], v[4:5], v[130:131] op_sel_hi:[1,0]
	v_pk_mul_f32 v[2:3], v[2:3], v[130:131] op_sel_hi:[1,0]
.Ld2x0_b:
	v_sub_f32_e32 v82, v82, v184
	v_exp_f32_e32 v82, v82
	v_sub_f32_e32 v83, v187, v184
	v_exp_f32_e32 v83, v83
	v_sub_f32_e32 v84, v84, v184
	v_exp_f32_e32 v84, v84
	v_sub_f32_e32 v85, v189, v184
	v_exp_f32_e32 v85, v85
	v_sub_f32_e32 v86, v86, v184
	v_add_f32_e32 v156, 0, v82
	v_exp_f32_e32 v86, v86
	v_sub_f32_e32 v87, v191, v184
	v_add_f32_e32 v156, v83, v156
	v_exp_f32_e32 v87, v87
	v_sub_f32_e32 v88, v88, v184
	v_add_f32_e32 v156, v84, v156
	v_exp_f32_e32 v88, v88
	v_sub_f32_e32 v89, v193, v184
	v_add_f32_e32 v156, v85, v156
	v_exp_f32_e32 v89, v89
	v_sub_f32_e32 v90, v90, v184
	v_add_f32_e32 v156, v86, v156
	v_exp_f32_e32 v90, v90
	v_sub_f32_e32 v91, v195, v184
	v_add_f32_e32 v156, v87, v156
	v_exp_f32_e32 v91, v91
	v_sub_f32_e32 v92, v92, v184
	v_add_f32_e32 v156, v88, v156
	v_exp_f32_e32 v92, v92
	v_sub_f32_e32 v93, v197, v184
	v_add_f32_e32 v156, v89, v156
	v_exp_f32_e32 v93, v93
	v_sub_f32_e32 v94, v94, v184
	v_add_f32_e32 v156, v90, v156
	v_exp_f32_e32 v94, v94
	v_sub_f32_e32 v95, v199, v184
	v_add_f32_e32 v156, v91, v156
	v_exp_f32_e32 v95, v95
	v_sub_f32_e32 v96, v96, v184
	v_add_f32_e32 v156, v92, v156
	v_exp_f32_e32 v96, v96
	v_sub_f32_e32 v97, v201, v184
	v_add_f32_e32 v156, v93, v156
	v_exp_f32_e32 v97, v97
	s_branch .Ld2x0_cv
; #define LAS __attribute__((address_space(3)))
; __device__ __forceinline__ unsigned pk2(float lo, float hi) { v2f v = {lo, hi}; return __builtin_bit_cast(unsigned, __builtin_convertvector(v, v2bf)); }
; __device__ __forceinline__ void d2_softmax(v16f& S, const float c1, const LAS float* tp, float& m, float& l, v16f (&O)[4], v8s (&P)[2]) {
;     float tmax = NEGBIG;
; #pragma unroll
;     for (int i = 0; i < 16; ++i) { S[i] = S[i] * c1 + tp[(i & 3) + 8 * (i >> 2)]; tmax = fmaxf(tmax, S[i]); }
;     tmax = fmaxf(tmax, __shfl_xor(tmax, 32));
;     const float mo = m;
;     if (__any(tmax > mo + 8.f)) {
;         const float mn = (tmax > mo + 8.f) ? tmax : mo;
;         const float alpha = __builtin_amdgcn_exp2f(mo - mn);
;         l *= alpha;
; #pragma unroll
;         for (int eb = 0; eb < 4; ++eb)
; #pragma unroll
;             for (int i = 0; i < 16; ++i) O[eb][i] *= alpha;
;         m = mn;
;     }
;     const float mc = m;
;     float ps = 0.f;
; #pragma unroll
;     for (int i = 0; i < 16; ++i) { S[i] = __builtin_amdgcn_exp2f(S[i] - mc); ps += S[i]; }
;     l += ps;
; #pragma unroll
;     for (int s2 = 0; s2 < 2; ++s2) { v4u w; w.x = pk2(S[8 * s2 + 0], S[8 * s2 + 1]); w.y = pk2(S[8 * s2 + 2], S[8 * s2 + 3]); w.z = pk2(S[8 * s2 + 4], S[8 * s2 + 5]); w.w = pk2(S[8 * s2 + 6], S[8 * s2 + 7]);
;         P[s2] = __builtin_bit_cast(v8s, w); }
; }
.Ld2x0_c1f:
	v_max3_f32 v158, v82, v83, v84
	v_max3_f32 v158, v158, v85, v86
	v_max3_f32 v158, v158, v87, v88
	v_max3_f32 v158, v158, v89, v90
	v_max3_f32 v158, v158, v91, v92
	v_max3_f32 v158, v158, v93, v94
	v_max3_f32 v158, v158, v95, v96
	v_max_f32_e32 v158, v158, v97
	v_fmamk_f32 v158, v158, 0x3e38aa3b, v186
	v_mov_b32_e32 v159, v158
	s_nop 1
	v_permlane32_swap_b32_e32 v159, v158
	v_max_f32_e32 v158, v158, v159
	v_cmp_gt_f32_e32 vcc, v158, v130
	s_cbranch_vccz .Ld2x0_f1a
	s_nop 0
	v_cndmask_b32_e32 v159, v184, v158, vcc
	v_sub_f32_e32 v158, v184, v159
	v_exp_f32_e32 v158, v158
	v_mov_b32_e32 v184, v159
	v_mul_f32_e32 v0, v0, v158
	v_pk_mul_f32 v[64:65], v[64:65], v[158:159] op_sel_hi:[1,0]
	v_pk_mul_f32 v[62:63], v[62:63], v[158:159] op_sel_hi:[1,0]
	v_pk_mul_f32 v[60:61], v[60:61], v[158:159] op_sel_hi:[1,0]
	v_pk_mul_f32 v[58:59], v[58:59], v[158:159] op_sel_hi:[1,0]
	v_pk_mul_f32 v[56:57], v[56:57], v[158:159] op_sel_hi:[1,0]
	v_pk_mul_f32 v[54:55], v[54:55], v[158:159] op_sel_hi:[1,0]
	v_pk_mul_f32 v[52:53], v[52:53], v[158:159] op_sel_hi:[1,0]
	v_pk_mul_f32 v[50:51], v[50:51], v[158:159] op_sel_hi:[1,0]
	v_pk_mul_f32 v[48:49], v[48:49], v[158:159] op_sel_hi:[1,0]
	v_pk_mul_f32 v[46:47], v[46:47], v[158:159] op_sel_hi:[1,0]
	v_pk_mul_f32 v[44:45], v[44:45], v[158:159] op_sel_hi:[1,0]
	v_pk_mul_f32 v[42:43], v[42:43], v[158:159] op_sel_hi:[1,0]
	v_pk_mul_f32 v[40:41], v[40:41], v[158:159] op_sel_hi:[1,0]
	v_pk_mul_f32 v[38:39], v[38:39], v[158:159] op_sel_hi:[1,0]
	v_pk_mul_f32 v[36:37], v[36:37], v[158:159] op_sel_hi:[1,0]
	v_pk_mul_f32 v[34:35], v[34:35], v[158:159] op_sel_hi:[1,0]
	v_pk_mul_f32 v[32:33], v[32:33], v[158:159] op_sel_hi:[1,0]
	v_pk_mul_f32 v[30:31], v[30:31], v[158:159] op_sel_hi:[1,0]
	v_pk_mul_f32 v[28:29], v[28:29], v[158:159] op_sel_hi:[1,0]
	v_pk_mul_f32 v[26:27], v[26:27], v[158:159] op_sel_hi:[1,0]
	v_pk_mul_f32 v[24:25], v[24:25], v[158:159] op_sel_hi:[1,0]
	v_pk_mul_f32 v[22:23], v[22:23], v[158:159] op_sel_hi:[1,0]
	v_pk_mul_f32 v[20:21], v[20:21], v[158:159] op_sel_hi:[1,0]
	v_pk_mul_f32 v[18:19], v[18:19], v[158:159] op_sel_hi:[1,0]
	v_pk_mul_f32 v[16:17], v[16:17], v[158:159] op_sel_hi:[1,0]
	v_pk_mul_f32 v[14:15], v[14:15], v[158:159] op_sel_hi:[1,0]
	v_pk_mul_f32 v[12:13], v[12:13], v[158:159] op_sel_hi:[1,0]
	v_pk_mul_f32 v[10:11], v[10:11], v[158:159] op_sel_hi:[1,0]
	v_pk_mul_f32 v[8:9], v[8:9], v[158:159] op_sel_hi:[1,0]
	v_pk_mul_f32 v[6:7], v[6:7], v[158:159] op_sel_hi:[1,0]
	v_pk_mul_f32 v[4:5], v[4:5], v[158:159] op_sel_hi:[1,0]
	v_pk_mul_f32 v[2:3], v[2:3], v[158:159] op_sel_hi:[1,0]
.Ld2x0_f1a:
	v_sub_f32_e32 v186, v186, v184
	v_fmamk_f32 v82, v82, 0x3e38aa3b, v186
	v_exp_f32_e32 v82, v82
	v_fmamk_f32 v83, v83, 0x3e38aa3b, v186
	v_exp_f32_e32 v83, v83
	v_fmamk_f32 v84, v84, 0x3e38aa3b, v186
	v_exp_f32_e32 v84, v84
	v_fmamk_f32 v85, v85, 0x3e38aa3b, v186
	v_exp_f32_e32 v85, v85
	v_fmamk_f32 v86, v86, 0x3e38aa3b, v186
	v_add_f32_e32 v156, 0, v82
	v_exp_f32_e32 v86, v86
	v_fmamk_f32 v87, v87, 0x3e38aa3b, v186
	v_add_f32_e32 v156, v83, v156
	v_exp_f32_e32 v87, v87
	v_fmamk_f32 v88, v88, 0x3e38aa3b, v186
	v_add_f32_e32 v156, v84, v156
	v_exp_f32_e32 v88, v88
	v_fmamk_f32 v89, v89, 0x3e38aa3b, v186
	v_add_f32_e32 v156, v85, v156
	v_exp_f32_e32 v89, v89
	v_fmamk_f32 v90, v90, 0x3e38aa3b, v186
	v_add_f32_e32 v156, v86, v156
	v_exp_f32_e32 v90, v90
	v_fmamk_f32 v91, v91, 0x3e38aa3b, v186
	v_add_f32_e32 v156, v87, v156
	v_exp_f32_e32 v91, v91
	v_fmamk_f32 v92, v92, 0x3e38aa3b, v186
	v_add_f32_e32 v156, v88, v156
	v_exp_f32_e32 v92, v92
	v_fmamk_f32 v93, v93, 0x3e38aa3b, v186
	v_add_f32_e32 v156, v89, v156
	v_exp_f32_e32 v93, v93
	v_fmamk_f32 v94, v94, 0x3e38aa3b, v186
	v_add_f32_e32 v156, v90, v156
	v_exp_f32_e32 v94, v94
	v_fmamk_f32 v95, v95, 0x3e38aa3b, v186
	v_add_f32_e32 v156, v91, v156
	v_exp_f32_e32 v95, v95
	v_fmamk_f32 v96, v96, 0x3e38aa3b, v186
	v_add_f32_e32 v156, v92, v156
	v_exp_f32_e32 v96, v96
	v_fmamk_f32 v97, v97, 0x3e38aa3b, v186
	v_add_f32_e32 v156, v93, v156
	v_exp_f32_e32 v97, v97
.Ld2x0_cv:
	v_cvt_pk_bf16_f32 v134, v66, v67
	v_add_f32_e32 v156, v94, v156
	v_cvt_pk_bf16_f32 v135, v68, v69
	v_add_f32_e32 v156, v95, v156
	v_cvt_pk_bf16_f32 v136, v70, v71
	v_add_f32_e32 v156, v96, v156
	v_cvt_pk_bf16_f32 v137, v72, v73
	v_add_f32_e32 v156, v97, v156
	v_cvt_pk_bf16_f32 v130, v74, v75
	v_cvt_pk_bf16_f32 v131, v76, v77
	v_cvt_pk_bf16_f32 v132, v78, v79
	v_cvt_pk_bf16_f32 v133, v80, v81
	v_add_f32_e32 v154, v0, v156
	v_cvt_pk_bf16_f32 v142, v82, v83
	v_cvt_pk_bf16_f32 v143, v84, v85
	v_cvt_pk_bf16_f32 v144, v86, v87
	v_cvt_pk_bf16_f32 v145, v88, v89
	v_cvt_pk_bf16_f32 v138, v90, v91
	v_cvt_pk_bf16_f32 v139, v92, v93
	v_cvt_pk_bf16_f32 v140, v94, v95
	v_cvt_pk_bf16_f32 v141, v96, v97
	s_setprio 0
.LBB0_341:
	s_or_b64 exec, exec, s[18:19]
	s_waitcnt lgkmcnt(0)
	s_barrier
	s_and_saveexec_b64 s[10:11], s[38:39]
	s_xor_b64 s[18:19], exec, s[10:11]
	s_cbranch_execz .LBB0_347
	s_setprio 3
	v_readfirstlane_b32 s98, v183
	v_med3_i32 v0, v183, s16, v214
	v_add_u32_e32 v156, 32, v183
	s_mov_b32 s100, 0xfff9f990
	s_mov_b32 s101, -1
	v_lshl_add_u32 v0, v0, 2, s23
	v_med3_i32 v156, v156, s16, v214
	s_add_i32 s99, s98, 32
	s_abs_i32 s98, s98
	s_abs_i32 s99, s99
	s_lshr_b32 s98, s98, 5
	s_lshr_b32 s99, s99, 5
	v_add_u32_e32 v0, 0xa80, v0
	v_lshl_add_u32 v156, v156, 2, s23
	v_add_u32_e32 v156, 0xa80, v156
	s_bitcmp1_b64 s[100:101], s99
	s_cbranch_scc1 .Ld2x1_i1f
	ds_read2_b32 v[186:187], v156 offset1:1
	ds_read2_b32 v[188:189], v156 offset0:2 offset1:3
	ds_read2_b32 v[190:191], v156 offset0:8 offset1:9
	ds_read2_b32 v[192:193], v156 offset0:10 offset1:11
	ds_read2_b32 v[194:195], v156 offset0:16 offset1:17
	ds_read2_b32 v[196:197], v156 offset0:18 offset1:19
	ds_read2_b32 v[198:199], v156 offset0:24 offset1:25
	ds_read2_b32 v[200:201], v156 offset0:26 offset1:27
	s_branch .Ld2x1_i1d

; #define LAS __attribute__((address_space(3)))
; __global__ void __launch_bounds__(512, 2) mega_fwd(Params p) {
;     extern __shared__ __attribute__((aligned(16))) unsigned char lds_raw[];
;     cg::grid_group grid = cg::this_grid();
;     LAS unsigned char* lds = (LAS unsigned char*)lds_raw;
;     const int tid = threadIdx.x, lane = tid & 63, wave = __builtin_amdgcn_readfirstlane(tid >> 6);
;     const int G = gridDim.x, bid = blockIdx.x;
;     const int gw = bid * 8 + wave, NGW = G * 8;
;     unsigned char* ws = p.ws;
;     bf16* Zb = (bf16*)(ws + WS_Z); bf16* Hb = (bf16*)(ws + WS_H);
;     if (tid < 16) ((LAS unsigned*)(lds + LDS_MISC))[tid] = 0u;
;     __syncthreads();
;     const XcdBarrier xbar = xcd_barrier_post((unsigned*)(ws + WS_BAR), (volatile LAS unsigned*)(lds + LDS_MISC));
	.amdhsa_kernel _Z8mega_fwd6Params
		.amdhsa_group_segment_fixed_size 0
		.amdhsa_private_segment_fixed_size 0
		.amdhsa_kernarg_size 376
		.amdhsa_user_sgpr_count 2
		.amdhsa_user_sgpr_dispatch_ptr 0
		.amdhsa_user_sgpr_queue_ptr 0
		.amdhsa_user_sgpr_kernarg_segment_ptr 1
		.amdhsa_user_sgpr_dispatch_id 0
		.amdhsa_user_sgpr_kernarg_preload_length 0
		.amdhsa_user_sgpr_kernarg_preload_offset 0
		.amdhsa_user_sgpr_private_segment_size 0
		.amdhsa_uses_dynamic_stack 0
		.amdhsa_enable_private_segment 0
		.amdhsa_system_sgpr_workgroup_id_x 1
		.amdhsa_system_sgpr_workgroup_id_y 0
		.amdhsa_system_sgpr_workgroup_id_z 0
		.amdhsa_system_sgpr_workgroup_info 0
		.amdhsa_system_vgpr_workitem_id 2
		.amdhsa_next_free_vgpr 252
		.amdhsa_next_free_sgpr 102
		.amdhsa_accum_offset 252
		.amdhsa_reserve_vcc 1
		.amdhsa_float_round_mode_32 0
		.amdhsa_float_round_mode_16_64 0
		.amdhsa_float_denorm_mode_32 3
		.amdhsa_float_denorm_mode_16_64 3
		.amdhsa_dx10_clamp 1
		.amdhsa_ieee_mode 1
		.amdhsa_fp16_overflow 0
		.amdhsa_tg_split 0
		.amdhsa_exception_fp_ieee_invalid_op 0
		.amdhsa_exception_fp_denorm_src 0
		.amdhsa_exception_fp_ieee_div_zero 0
		.amdhsa_exception_fp_ieee_overflow 0
		.amdhsa_exception_fp_ieee_underflow 0
		.amdhsa_exception_fp_ieee_inexact 0
		.amdhsa_exception_int_div_zero 0
	.end_amdhsa_kernel

; __global__ void __launch_bounds__(512, 2) mega_fwd(Params p) {
amdhsa.kernels:
  - .agpr_count:     0
    .args:
      - .offset:         0
        .size:           120
        .value_kind:     by_value
      - .offset:         120
        .size:           4
        .value_kind:     hidden_block_count_x
      - .offset:         124
        .size:           4
        .value_kind:     hidden_block_count_y
      - .offset:         128
        .size:           4
        .value_kind:     hidden_block_count_z
      - .offset:         132
        .size:           2
        .value_kind:     hidden_group_size_x
      - .offset:         134
        .size:           2
        .value_kind:     hidden_group_size_y
      - .offset:         136
        .size:           2
        .value_kind:     hidden_group_size_z
      - .offset:         138
        .size:           2
        .value_kind:     hidden_remainder_x
      - .offset:         140
        .size:           2
        .value_kind:     hidden_remainder_y
      - .offset:         142
        .size:           2
        .value_kind:     hidden_remainder_z
      - .offset:         160
        .size:           8
        .value_kind:     hidden_global_offset_x
      - .offset:         168
        .size:           8
        .value_kind:     hidden_global_offset_y
      - .offset:         176
        .size:           8
        .value_kind:     hidden_global_offset_z
      - .offset:         184
        .size:           2
        .value_kind:     hidden_grid_dims
      - .offset:         208
        .size:           8
        .value_kind:     hidden_multigrid_sync_arg
      - .offset:         240
        .size:           4
        .value_kind:     hidden_dynamic_lds_size
    .group_segment_fixed_size: 0
    .kernarg_segment_align: 8
    .kernarg_segment_size: 376
    .language:       OpenCL C
    .language_version:
      - 2
      - 0
    .max_flat_workgroup_size: 512
    .name:           _Z8mega_fwd6Params
    .private_segment_fixed_size: 0
    .sgpr_count:     108
    .sgpr_spill_count: 223
    .symbol:         _Z8mega_fwd6Params.kd
    .uniform_work_group_size: 1
    .uses_dynamic_stack: false
    .vgpr_count:     252
    .vgpr_spill_count: 0
    .wavefront_size: 64
